# residual GEMM done(): owner-XCC byte load issued behind the tile's last store so one vmcnt wait covers both (one L2 round trip less per tile)
# speedup vs baseline: 1.0091x; 1.0014x over previous
;     __device__ __forceinline__ void done(const pg8::Unit& u) const {
;         asm volatile("s_waitcnt vmcnt(0)" ::: "memory");
;         const int owner = (u.pm >> 5) + 8 * ((u.pm & 7) + 8 * ((u.pm >> 3) & 3));
;         if ((unsigned)xcc_of[owner] != myx) { __builtin_amdgcn_fence(__ATOMIC_RELEASE, "agent"); asm volatile("s_waitcnt vmcnt(0)" ::: "memory"); }
;         if ((threadIdx.x & 63) == 0) __hip_atomic_fetch_add(cnt + 16 * u.pm, 1u, __ATOMIC_RELAXED, __HIP_MEMORY_SCOPE_AGENT);
;     __device__ __forceinline__ void operator()(const f32x4 (&acc)[2][2][4][2], const Unit& u, int wr, int wc, int fr, int fq) const {
;     ...
;             for (int m2 = 0; m2 < 2; ++m2) {
;                 const int m = 2 * mh + m2;
;                 const size_t off = (size_t)(row0 + ai * 128 + m * 16) * DM + col0;
; #pragma unroll
;                 for (int bj = 0; bj < 2; ++bj)
; #pragma unroll
;                     for (int n = 0; n < 2; ++n) {
;                         const f32x4 x = (xv[m2][bj][n] - ms[m2].x) * ms[m2].y * gv[bj][n] + bv[bj][n];
;                         *(f32x4*)(dst + off + bj * 128 + n * 16) = x * DN_ALPHA + acc[ai][bj][m][n] * scale;
;                     }
;             }
;             asm volatile("" ::: "memory");
.LBB0_662:
	v_lshlrev_b64 v[68:69], 12, v[60:61]
	v_lshl_add_u64 v[70:71], v[224:225], 0, v[68:69]
	global_load_dwordx4 v[60:63], v[70:71], off
	global_load_dwordx4 v[64:67], v[70:71], off offset:64
	s_waitcnt vmcnt(5)
	v_cndmask_b32_e64 v54, v57, v54, s[12:13]
	v_sub_f32_e32 v73, v49, v56
	v_sub_f32_e32 v72, v48, v56
	v_sub_f32_e32 v75, v47, v56
	v_sub_f32_e32 v74, v46, v56
	global_load_dwordx4 v[46:49], v[70:71], off offset:512
	s_waitcnt vmcnt(5)
	v_sub_f32_e32 v45, v45, v56
	v_sub_f32_e32 v44, v44, v56
	v_sub_f32_e32 v43, v43, v56
	v_sub_f32_e32 v42, v42, v56
	s_waitcnt vmcnt(4)
	v_sub_f32_e32 v41, v41, v56
	v_sub_f32_e32 v40, v40, v56
	v_sub_f32_e32 v39, v39, v56
	v_sub_f32_e32 v38, v38, v56
	s_waitcnt vmcnt(3)
	v_cndmask_b32_e64 v50, v53, v50, s[12:13]
	v_sub_f32_e32 v77, v37, v56
	v_sub_f32_e32 v76, v36, v56
	v_sub_f32_e32 v57, v35, v56
	v_sub_f32_e32 v56, v34, v56
	global_load_dwordx4 v[34:37], v[70:71], off offset:576
	v_pk_mul_f32 v[70:71], v[54:55], v[74:75] op_sel_hi:[0,1]
	v_pk_mul_f32 v[72:73], v[54:55], v[72:73] op_sel_hi:[0,1]
	v_pk_mul_f32 v[38:39], v[54:55], v[38:39] op_sel_hi:[0,1]
	v_pk_mul_f32 v[40:41], v[54:55], v[40:41] op_sel_hi:[0,1]
	v_pk_mul_f32 v[42:43], v[54:55], v[42:43] op_sel_hi:[0,1]
	v_pk_mul_f32 v[44:45], v[54:55], v[44:45] op_sel_hi:[0,1]
	v_pk_mul_f32 v[56:57], v[54:55], v[56:57] op_sel_hi:[0,1]
	v_pk_mul_f32 v[54:55], v[54:55], v[76:77] op_sel_hi:[0,1]
	v_pk_fma_f32 v[72:73], v[108:109], v[72:73], v[112:113]
	v_pk_fma_f32 v[70:71], v[106:107], v[70:71], v[110:111]
	v_pk_fma_f32 v[40:41], v[124:125], v[40:41], v[128:129]
	v_pk_fma_f32 v[38:39], v[122:123], v[38:39], v[126:127]
	v_mov_b32_e32 v211, v210
	v_lshl_add_u64 v[58:59], s[48:49], 0, v[58:59]
	v_pk_fma_f32 v[44:45], v[100:101], v[44:45], v[104:105]
	v_pk_fma_f32 v[42:43], v[98:99], v[42:43], v[102:103]
	v_pk_fma_f32 v[54:55], v[116:117], v[54:55], v[120:121]
	v_pk_fma_f32 v[56:57], v[114:115], v[56:57], v[118:119]
	v_pk_mul_f32 v[70:71], v[70:71], s[88:89] op_sel_hi:[1,0]
	v_pk_mul_f32 v[72:73], v[72:73], s[88:89] op_sel_hi:[1,0]
	v_pk_mul_f32 v[38:39], v[38:39], s[88:89] op_sel_hi:[1,0]
	v_pk_mul_f32 v[40:41], v[40:41], s[88:89] op_sel_hi:[1,0]
	v_lshl_add_u64 v[58:59], v[58:59], 0, v[220:221]
	v_pk_mul_f32 v[42:43], v[42:43], s[88:89] op_sel_hi:[1,0]
	v_pk_mul_f32 v[44:45], v[44:45], s[88:89] op_sel_hi:[1,0]
	v_pk_mul_f32 v[56:57], v[56:57], s[88:89] op_sel_hi:[1,0]
	v_pk_mul_f32 v[54:55], v[54:55], s[88:89] op_sel_hi:[1,0]
	v_pk_fma_f32 v[32:33], v[32:33], v[210:211], v[72:73]
	v_pk_fma_f32 v[30:31], v[30:31], v[214:215], v[70:71]
	v_pk_fma_f32 v[24:25], v[24:25], v[210:211], v[40:41]
	v_pk_fma_f32 v[22:23], v[22:23], v[214:215], v[38:39]
	v_pk_fma_f32 v[28:29], v[28:29], v[210:211], v[44:45]
	v_pk_fma_f32 v[26:27], v[26:27], v[214:215], v[42:43]
	v_pk_fma_f32 v[20:21], v[20:21], v[210:211], v[54:55]
	v_pk_fma_f32 v[18:19], v[18:19], v[214:215], v[56:57]
	global_store_dwordx4 v[58:59], v[30:33], off
	global_store_dwordx4 v[58:59], v[26:29], off offset:64
	global_store_dwordx4 v[58:59], v[22:25], off offset:512
	global_store_dwordx4 v[58:59], v[18:21], off offset:576
	v_lshl_add_u64 v[68:69], s[48:49], 0, v[68:69]
	v_lshl_add_u64 v[68:69], v[68:69], 0, v[220:221]
	s_lshl_b32 s13, s44, 3
	s_ashr_i32 s12, s44, 5
	s_and_b32 s13, s13, 0xf8
	s_add_i32 s13, s13, s12
	s_ashr_i32 s33, s13, 31
	s_add_u32 s12, s90, s13
	s_addc_u32 s13, s91, s33
	s_waitcnt vmcnt(7)
	v_sub_f32_e32 v19, v63, v52
	s_waitcnt vmcnt(6)
	v_sub_f32_e32 v23, v67, v52
	v_sub_f32_e32 v22, v66, v52
	v_sub_f32_e32 v25, v65, v52
	v_sub_f32_e32 v24, v64, v52
	v_pk_mul_f32 v[24:25], v[50:51], v[24:25] op_sel_hi:[0,1]
	v_pk_mul_f32 v[22:23], v[50:51], v[22:23] op_sel_hi:[0,1]
	v_pk_fma_f32 v[22:23], v[100:101], v[22:23], v[104:105]
	v_pk_fma_f32 v[24:25], v[98:99], v[24:25], v[102:103]
	v_pk_mul_f32 v[22:23], v[22:23], s[88:89] op_sel_hi:[1,0]
	v_pk_mul_f32 v[24:25], v[24:25], s[88:89] op_sel_hi:[1,0]
	v_pk_fma_f32 v[12:13], v[12:13], v[210:211], v[22:23]
	v_pk_fma_f32 v[10:11], v[10:11], v[214:215], v[24:25]
	global_store_dwordx4 v[68:69], v[10:13], off offset:64
	v_sub_f32_e32 v18, v62, v52
	v_sub_f32_e32 v21, v61, v52
	s_waitcnt vmcnt(6)
	v_sub_f32_e32 v11, v49, v52
	v_sub_f32_e32 v10, v48, v52
	v_sub_f32_e32 v13, v47, v52
	v_sub_f32_e32 v12, v46, v52
	v_pk_mul_f32 v[12:13], v[50:51], v[12:13] op_sel_hi:[0,1]
	v_pk_mul_f32 v[10:11], v[50:51], v[10:11] op_sel_hi:[0,1]
	v_pk_fma_f32 v[10:11], v[124:125], v[10:11], v[128:129]
	v_pk_fma_f32 v[12:13], v[122:123], v[12:13], v[126:127]
	v_pk_mul_f32 v[10:11], v[10:11], s[88:89] op_sel_hi:[1,0]
	v_pk_mul_f32 v[12:13], v[12:13], s[88:89] op_sel_hi:[1,0]
	v_pk_fma_f32 v[8:9], v[8:9], v[210:211], v[10:11]
	v_pk_fma_f32 v[6:7], v[6:7], v[214:215], v[12:13]
	v_sub_f32_e32 v20, v60, v52
	global_store_dwordx4 v[68:69], v[6:9], off offset:512
	v_pk_mul_f32 v[20:21], v[50:51], v[20:21] op_sel_hi:[0,1]
	v_pk_mul_f32 v[18:19], v[50:51], v[18:19] op_sel_hi:[0,1]
	s_waitcnt vmcnt(6)
	v_sub_f32_e32 v7, v37, v52
	v_sub_f32_e32 v6, v36, v52
	v_sub_f32_e32 v9, v35, v52
	v_sub_f32_e32 v8, v34, v52
	v_pk_mul_f32 v[8:9], v[50:51], v[8:9] op_sel_hi:[0,1]
	v_pk_mul_f32 v[6:7], v[50:51], v[6:7] op_sel_hi:[0,1]
	v_pk_fma_f32 v[18:19], v[108:109], v[18:19], v[112:113]
	v_pk_fma_f32 v[20:21], v[106:107], v[20:21], v[110:111]
	v_pk_fma_f32 v[6:7], v[116:117], v[6:7], v[120:121]
	v_pk_fma_f32 v[8:9], v[114:115], v[8:9], v[118:119]
	v_pk_mul_f32 v[20:21], v[20:21], s[88:89] op_sel_hi:[1,0]
	v_pk_mul_f32 v[18:19], v[18:19], s[88:89] op_sel_hi:[1,0]
	v_pk_mul_f32 v[8:9], v[8:9], s[88:89] op_sel_hi:[1,0]
	v_pk_mul_f32 v[6:7], v[6:7], s[88:89] op_sel_hi:[1,0]
	v_pk_fma_f32 v[16:17], v[16:17], v[210:211], v[18:19]
	v_pk_fma_f32 v[14:15], v[14:15], v[214:215], v[20:21]
	v_pk_fma_f32 v[4:5], v[4:5], v[210:211], v[6:7]
	v_pk_fma_f32 v[2:3], v[2:3], v[214:215], v[8:9]
	global_store_dwordx4 v[68:69], v[14:17], off
	global_store_dwordx4 v[68:69], v[2:5], off offset:576
	global_load_ubyte v30, v1, s[12:13]
	s_waitcnt vmcnt(0)
	v_cmp_eq_u32_e32 vcc, s96, v30
	s_cbranch_vccnz .LBB0_664
	buffer_wbl2 sc1
	s_waitcnt vmcnt(0)
